# v24 plus next-item indexer-q fragments loaded one item ahead
# baseline (speedup 1.0000x reference)
; template <bool DUMMY> __device__ __forceinline__ void phase_dsa(const Args& a, unsigned char* lds) {
;     unsigned char* ws = a.ws;
;     bf16_t* P = (bf16_t*)(ws + WS_P); const float* SM = (const float*)(ws + WS_SM);
;     const bf16_t* IKC = (const bf16_t*)(ws + WS_IKC); const bf16_t* KVC = (const bf16_t*)(ws + WS_KVC);
;     constexpr int SCS = 8200;
;     float* SC = (float*)lds;
;     unsigned* HIST = (unsigned*)(lds + 131200);
;     int* LIST = (int*)(lds + 131200 + 16384);
;     unsigned* QS = (unsigned*)(lds + 131200 + 16384 + 4096);
;     int* CNT = (int*)(lds + 131200 + 16384 + 4096 + 4096);
;     const float idx_scale = 0.125f * 0.35355339059327373f;
;     f32x4 wqv[2]; unsigned qsv[2];
;     ...
;     if ((int)blockIdx.x < 16384) DSA_LOAD_ITEM(blockIdx.x);
;     for (int item = blockIdx.x; item < 16384; item += gridDim.x) {
;         int tid_ = threadIdx.x; asm volatile("" : "+v"(tid_));
;         const int tid = tid_, wave = __builtin_amdgcn_readfirstlane(tid >> 6), lane = tid & 63, quad = lane >> 4, l15 = lane & 15;
;         const int b = item & 7, tq = item >> 3, t0 = tq * 4, L = ((t0 >> 6) + 1) * 64;
;         const size_t r0 = (size_t)b * SEQ + t0;
;         const bool do_sel = (L > 256) && !DBG_NOSEL;
.LBB0_858:
	s_mov_b32 s92, 1
	s_mov_b32 s4, 0
	s_mov_b32 s6, s4
	s_mov_b32 s7, s4
	s_add_u32 s19, s70, 0x34800000
	s_mov_b32 s5, s4
	v_mov_b64_e32 v[248:249], s[6:7]
	v_mov_b32_e32 v9, 0
	v_mbcnt_hi_u32_b32 v218, -1, v157
	s_addc_u32 s36, s71, 0
	v_mov_b64_e32 v[246:247], s[4:5]
	s_add_i32 s37, 0, 0x26080
	s_movk_i32 s38, 0x2800
	s_movk_i32 s39, 0xff
	s_movk_i32 s40, 0x100
	s_mov_b32 s41, 0x8020
	s_movk_i32 s42, 0x1c1
	s_movk_i32 s43, 0x1c0
	s_movk_i32 s48, 0xbf
	v_mov_b32_e32 v159, 1
	s_mov_b32 s49, 0x7ffffeff
	v_mov_b32_e32 v216, 0x100
	s_movk_i32 s50, 0x90
	s_mov_b32 s18, 0x3e000000
	s_mov_b32 s51, 0xff800000
	v_mov_b32_e32 v217, 0x10000
	v_and_b32_e32 v219, 64, v218
	v_mov_b32_e32 v250, v9
	v_mov_b32_e32 v251, v9
	s_mov_b32 s52, s2
	s_waitcnt vmcnt(0)
	s_branch .LBB0_860

; #define IDX_LOAD(BUF, G) do { _Pragma("unroll") for (int tt = 0; tt < 4; ++tt) _Pragma("unroll") for (int ks = 0; ks < 2; ++ks) \
;                 BUF[tt][ks] = *(const bf16x8*)(ikb + (size_t)(((G) * 4 + tt) * 8 + ks * 4) * 128); } while (0)
; template <bool DUMMY> __device__ __forceinline__ void phase_dsa(const Args& a, unsigned char* lds) {
;     ...
;         { u32x4* hz = (u32x4*)HIST; hz[tid] = (u32x4){0u, 0u, 0u, 0u}; hz[tid + 512] = (u32x4){0u, 0u, 0u, 0u}; }
;         if (tid < 8) CNT[4 + tid] = 0;
;         QS[tid] = qsv[0]; QS[tid + 512] = qsv[1];
;         float wq[8];
; #pragma unroll
;         for (int h = 0; h < 4; ++h) { wq[h] = wqv[0][h] * idx_scale; wq[4 + h] = wqv[1][h] * idx_scale; }
;         bf16x8 af[2][2];
; #pragma unroll
;         for (int T = 0; T < 2; ++T)
; #pragma unroll
;             for (int ks = 0; ks < 2; ++ks) af[T][ks] = *(const bf16x8*)(P + (r0 + (l15 >> 2)) * LDP + C_IQ + (4 * T + (l15 & 3)) * 64 + ks * 32 + quad * 8);
;         const int ngroups = L >> 6;
;         const bf16_t* ikb = IKC + (size_t)b * SEQ * 64 + (quad * 16 + l15) * 8;
;         bf16x8 B0[4][2], B1[4][2], B2[4][2];
;     ...
;         if (wave < ngroups) IDX_LOAD(B0, wave);
;         if (wave + 8 < ngroups) IDX_LOAD(B1, wave + 8);
;         if (wave + 16 < ngroups) IDX_LOAD(B2, wave + 16);
.Ldsa_nz:
	s_and_saveexec_b64 s[0:1], vcc
	v_lshl_add_u32 v8, v124, 2, s37
	ds_write_b32 v8, v9 offset:16
	s_or_b64 exec, exec, s[0:1]
	s_ashr_i32 s22, s52, 1
	s_and_b32 s0, s22, -4
	s_andn2_b32 s22, s22, 63
	s_lshl_b32 s1, s52, 13
	s_ashr_i32 s63, s62, 6
	s_add_i32 s12, s22, 64
	s_and_b32 s64, s1, 0xe000
	s_ashr_i32 s4, s0, 31
	s_add_u32 s53, s64, s0
	v_bfe_u32 v8, v124, 2, 2
	v_or_b32_e32 v8, s53, v8
	v_mov_b64_e32 v[10:11], s[44:45]
	v_mad_i64_i32 v[10:11], s[0:1], v8, s38, v[10:11]
	v_and_b32_e32 v8, 48, v124
	v_lshl_add_u64 v[10:11], v[10:11], 0, v[8:9]
	v_lshlrev_b32_e32 v8, 7, v124
	v_and_b32_e32 v8, 0x180, v8
	v_lshl_add_u64 v[10:11], v[10:11], 0, v[8:9]
	v_mov_b64_e32 v[108:109], v[60:61]
	v_mov_b64_e32 v[110:111], v[62:63]
	v_mov_b64_e32 v[112:113], v[64:65]
	v_mov_b64_e32 v[114:115], v[66:67]
	v_mov_b64_e32 v[116:117], v[68:69]
	v_mov_b64_e32 v[118:119], v[70:71]
	v_mov_b64_e32 v[120:121], v[72:73]
	v_mov_b64_e32 v[122:123], v[74:75]
	s_addc_u32 s60, 0, s4
	v_lshl_add_u32 v8, v124, 2, 0
	s_ashr_i32 s13, s12, 6
	s_lshl_b32 s0, s64, 7
	v_add_u32_e32 v8, 0x25080, v8
	s_add_u32 s0, s56, s0
	s_waitcnt vmcnt(4)
	ds_write2st64_b32 v8, v220, v221 offset1:8
	s_addc_u32 s1, s57, 0
	v_lshlrev_b32_e32 v8, 4, v124
	v_and_b32_e32 v8, 0x3f0, v8
	s_cmp_lt_i32 s63, s13
	s_cselect_b64 s[4:5], -1, 0
	s_cmp_ge_i32 s63, s13
	v_lshl_add_u64 v[10:11], s[0:1], 0, v[8:9]
	s_cbranch_scc1 .LBB0_902
	s_lshl_b32 s0, s63, 5
	s_ashr_i32 s1, s0, 31
	s_lshl_b64 s[6:7], s[0:1], 8
	v_lshl_add_u64 v[12:13], v[10:11], 0, s[6:7]
	s_or_b32 s6, s0, 4
	s_ashr_i32 s7, s6, 31
	s_lshl_b64 s[6:7], s[6:7], 8
	v_lshl_add_u64 v[32:33], v[10:11], 0, s[6:7]
	s_or_b32 s6, s0, 8
	s_ashr_i32 s7, s6, 31
	s_lshl_b64 s[6:7], s[6:7], 8
	v_lshl_add_u64 v[52:53], v[10:11], 0, s[6:7]
	s_or_b32 s6, s0, 12
	s_ashr_i32 s7, s6, 31
	s_lshl_b64 s[6:7], s[6:7], 8
	v_lshl_add_u64 v[56:57], v[10:11], 0, s[6:7]
	s_or_b32 s6, s0, 16
	s_ashr_i32 s7, s6, 31
	s_lshl_b64 s[6:7], s[6:7], 8
	v_lshl_add_u64 v[76:77], v[10:11], 0, s[6:7]
	s_or_b32 s6, s0, 20
	s_ashr_i32 s7, s6, 31
	s_lshl_b64 s[6:7], s[6:7], 8
	v_lshl_add_u64 v[80:81], v[10:11], 0, s[6:7]
	s_or_b32 s6, s0, 24
	s_or_b32 s0, s0, 28
	s_ashr_i32 s7, s6, 31
	s_ashr_i32 s1, s0, 31
	s_lshl_b64 s[6:7], s[6:7], 8
	s_lshl_b64 s[0:1], s[0:1], 8
	v_lshl_add_u64 v[100:101], v[10:11], 0, s[6:7]
	v_lshl_add_u64 v[104:105], v[10:11], 0, s[0:1]
	global_load_dwordx4 v[12:15], v[12:13], off
	s_nop 0
	global_load_dwordx4 v[32:35], v[32:33], off
	s_nop 0
	global_load_dwordx4 v[52:55], v[52:53], off
	s_nop 0
	global_load_dwordx4 v[56:59], v[56:57], off
	s_nop 0
	global_load_dwordx4 v[76:79], v[76:77], off
	s_nop 0
	global_load_dwordx4 v[80:83], v[80:81], off
	s_nop 0
	global_load_dwordx4 v[100:103], v[100:101], off
	s_nop 0
	global_load_dwordx4 v[104:107], v[104:105], off
	s_add_i32 s0, s63, 8
	s_cmp_ge_i32 s0, s13
	s_cbranch_scc0 .LBB0_903
